# speedup vs baseline: 1.0068x; 1.0068x over previous
; __device__ __forceinline__ unsigned cvt_pk(float lo, float hi) { unsigned r; asm("v_cvt_pk_bf16_f32 %0, %1, %2" : "=v"(r) : "v"(lo), "v"(hi)); return r; }
; __device__ __forceinline__ void gla_a_item(unsigned char* lds, const Params& p, int item) {
;     ...
;         const float* s0p = p.in[4] + (size_t)sidx * 32768; float* so = p.out + O_GS + (size_t)sidx * 32768;
;         bf16_t* STS = (bf16_t*)(p.ws + WS_STS) + (size_t)sidx * 32768;
; #pragma unroll
;         for (int kb = 0; kb < 8; ++kb)
; #pragma unroll
;             for (int v = 0; v < 2; ++v) { const int vdim = 16 * (2 * wave + v) + li, kdim = 16 * kb + 4 * fq; float s0[4];
; #pragma unroll
;                 for (int r = 0; r < 4; ++r) { s0[r] = s0p[(size_t)(kdim + r) * 256 + vdim]; so[(size_t)(kdim + r) * 256 + vdim] = s0[r] * __expf(bl[kdim + r]) + acc[kb][v][r]; }
;                 u32x2 w; w.x = cvt_pk(s0[0], s0[1]); w.y = cvt_pk(s0[2], s0[3]); *(u32x2*)(STS + vdim * 128 + kdim) = w; asm volatile("" ::: "memory"); }
.LBB0_777:
	s_andn2_b64 vcc, exec, s[0:1]
	s_cbranch_vccnz .LBB0_779
	v_readlane_b32 s8, v251, 18
	v_readlane_b32 s9, v251, 19
	v_readlane_b32 s10, v251, 20
	v_readlane_b32 s11, v251, 21
	v_readlane_b32 s12, v251, 22
	v_readlane_b32 s13, v251, 23
	v_readlane_b32 s14, v251, 24
	v_readlane_b32 s15, v251, 25
	s_ashr_i32 s5, s4, 31
	v_readlane_b32 s16, v251, 26
	v_readlane_b32 s17, v251, 27
	v_readlane_b32 s18, v251, 28
	v_readlane_b32 s19, v251, 29
	s_mov_b64 s[8:9], s[12:13]
	s_lshl_b64 s[0:1], s[4:5], 17
	s_mov_b64 s[10:11], s[14:15]
	s_mov_b64 s[12:13], s[16:17]
	s_add_u32 s2, s12, s0
	s_addc_u32 s3, s13, s1
	v_readlane_b32 s6, v252, 15
	s_add_u32 s0, s6, s0
	v_readlane_b32 s6, v252, 17
	s_addc_u32 s1, s6, s1
	s_lshl_b64 s[4:5], s[4:5], 16
	v_readlane_b32 s6, v252, 19
	s_add_u32 s4, s6, s4
	v_readlane_b32 s6, v252, 21
	s_addc_u32 s5, s6, s5
	v_lshl_add_u64 v[64:65], s[4:5], 0, v[76:77]
	v_lshlrev_b32_e32 v76, 10, v69
	v_ashrrev_i32_e32 v71, 31, v70
	v_lshl_add_u64 v[66:67], v[70:71], 0, v[76:77]
	v_lshlrev_b64 v[72:73], 2, v[66:67]
	v_lshl_add_u64 v[66:67], s[2:3], 0, v[72:73]
	v_mov_b32_e32 v142, v66
	v_mov_b32_e32 v143, v67
	global_load_dword v144, v[142:143], off
	global_load_dword v145, v[142:143], off offset:64
	global_load_dword v146, v[142:143], off offset:1024
	global_load_dword v147, v[142:143], off offset:1088
	global_load_dword v148, v[142:143], off offset:2048
	global_load_dword v149, v[142:143], off offset:2112
	global_load_dword v150, v[142:143], off offset:3072
	global_load_dword v151, v[142:143], off offset:3136
	v_add_co_u32_e32 v142, vcc, 0x4000, v142
	s_nop 1
	v_addc_co_u32_e32 v143, vcc, 0, v143, vcc
	global_load_dword v144, v[142:143], off
	global_load_dword v145, v[142:143], off offset:64
	global_load_dword v146, v[142:143], off offset:1024
	global_load_dword v147, v[142:143], off offset:1088
	global_load_dword v148, v[142:143], off offset:2048
	global_load_dword v149, v[142:143], off offset:2112
	global_load_dword v150, v[142:143], off offset:3072
	global_load_dword v151, v[142:143], off offset:3136
	v_add_co_u32_e32 v142, vcc, 0x4000, v142
	s_nop 1
	v_addc_co_u32_e32 v143, vcc, 0, v143, vcc
	global_load_dword v144, v[142:143], off
	global_load_dword v145, v[142:143], off offset:64
	global_load_dword v146, v[142:143], off offset:1024
	global_load_dword v147, v[142:143], off offset:1088
	global_load_dword v148, v[142:143], off offset:2048
	global_load_dword v149, v[142:143], off offset:2112
	global_load_dword v150, v[142:143], off offset:3072
	global_load_dword v151, v[142:143], off offset:3136
	v_add_co_u32_e32 v142, vcc, 0x4000, v142
	s_nop 1
	v_addc_co_u32_e32 v143, vcc, 0, v143, vcc
	global_load_dword v144, v[142:143], off
	global_load_dword v145, v[142:143], off offset:64
	global_load_dword v146, v[142:143], off offset:1024
	global_load_dword v147, v[142:143], off offset:1088
	global_load_dword v148, v[142:143], off offset:2048
	global_load_dword v149, v[142:143], off offset:2112
	global_load_dword v150, v[142:143], off offset:3072
	global_load_dword v151, v[142:143], off offset:3136
	v_add_co_u32_e32 v142, vcc, 0x4000, v142
	s_nop 1
	v_addc_co_u32_e32 v143, vcc, 0, v143, vcc
	global_load_dword v144, v[142:143], off
	global_load_dword v145, v[142:143], off offset:64
	global_load_dword v146, v[142:143], off offset:1024
	global_load_dword v147, v[142:143], off offset:1088
	global_load_dword v148, v[142:143], off offset:2048
	global_load_dword v149, v[142:143], off offset:2112
	global_load_dword v150, v[142:143], off offset:3072
	global_load_dword v151, v[142:143], off offset:3136
	v_add_co_u32_e32 v142, vcc, 0x4000, v142
	s_nop 1
	v_addc_co_u32_e32 v143, vcc, 0, v143, vcc
	global_load_dword v144, v[142:143], off
	global_load_dword v145, v[142:143], off offset:64
	global_load_dword v146, v[142:143], off offset:1024
	global_load_dword v147, v[142:143], off offset:1088
	global_load_dword v148, v[142:143], off offset:2048
	global_load_dword v149, v[142:143], off offset:2112
	global_load_dword v150, v[142:143], off offset:3072
	global_load_dword v151, v[142:143], off offset:3136
	v_add_co_u32_e32 v142, vcc, 0x4000, v142
	s_nop 1
	v_addc_co_u32_e32 v143, vcc, 0, v143, vcc
	global_load_dword v144, v[142:143], off
	global_load_dword v145, v[142:143], off offset:64
	global_load_dword v146, v[142:143], off offset:1024
	global_load_dword v147, v[142:143], off offset:1088
	global_load_dword v148, v[142:143], off offset:2048
	global_load_dword v149, v[142:143], off offset:2112
	global_load_dword v150, v[142:143], off offset:3072
	global_load_dword v151, v[142:143], off offset:3136
	v_add_co_u32_e32 v142, vcc, 0x4000, v142
	s_nop 1
	v_addc_co_u32_e32 v143, vcc, 0, v143, vcc
	global_load_dword v144, v[142:143], off
	global_load_dword v145, v[142:143], off offset:64
	global_load_dword v146, v[142:143], off offset:1024
	global_load_dword v147, v[142:143], off offset:1088
	global_load_dword v148, v[142:143], off offset:2048
	global_load_dword v149, v[142:143], off offset:2112
	global_load_dword v150, v[142:143], off offset:3072
	global_load_dword v151, v[142:143], off offset:3136
	global_load_dword v69, v[66:67], off
	ds_read_b128 v[78:81], v68 offset:6144
	v_mov_b32_e32 v75, v77
	v_lshl_add_u64 v[72:73], s[0:1], 0, v[72:73]
	v_lshlrev_b32_e32 v92, 7, v70
	v_ashrrev_i32_e32 v93, 31, v92
	s_waitcnt lgkmcnt(0)
	v_mul_f32_e32 v74, 0x3fb8aa3b, v78
	v_exp_f32_e32 v74, v74
	v_mul_f32_e32 v80, 0x3fb8aa3b, v80
	v_exp_f32_e32 v80, v80
	v_readlane_b32 s20, v251, 30
	v_readlane_b32 s21, v251, 31
	v_readlane_b32 s22, v251, 32
	v_readlane_b32 s23, v251, 33
	s_mov_b64 s[14:15], s[18:19]
	s_waitcnt vmcnt(0)
; __device__ __forceinline__ unsigned cvt_pk(float lo, float hi) { unsigned r; asm("v_cvt_pk_bf16_f32 %0, %1, %2" : "=v"(r) : "v"(lo), "v"(hi)); return r; }
; __device__ __forceinline__ void gla_a_item(unsigned char* lds, const Params& p, int item) {
;     ...
;         for (int kb = 0; kb < 8; ++kb)
; #pragma unroll
;             for (int v = 0; v < 2; ++v) { const int vdim = 16 * (2 * wave + v) + li, kdim = 16 * kb + 4 * fq; float s0[4];
; #pragma unroll
;                 for (int r = 0; r < 4; ++r) { s0[r] = s0p[(size_t)(kdim + r) * 256 + vdim]; so[(size_t)(kdim + r) * 256 + vdim] = s0[r] * __expf(bl[kdim + r]) + acc[kb][v][r]; }
;                 u32x2 w; w.x = cvt_pk(s0[0], s0[1]); w.y = cvt_pk(s0[2], s0[3]); *(u32x2*)(STS + vdim * 128 + kdim) = w; asm volatile("" ::: "memory"); }
	v_fma_f32 v60, v69, v74, v60
	v_or_b32_e32 v74, 0x100, v76
	v_lshl_add_u64 v[74:75], v[74:75], 0, v[70:71]
	v_lshlrev_b64 v[74:75], 2, v[74:75]
	global_store_dword v[72:73], v60, off
	v_lshl_add_u64 v[82:83], s[2:3], 0, v[74:75]
	global_load_dword v78, v[82:83], off
	v_mul_f32_e32 v60, 0x3fb8aa3b, v79
	v_exp_f32_e32 v60, v60
	v_lshl_add_u64 v[74:75], s[0:1], 0, v[74:75]
	s_waitcnt vmcnt(0)
	v_fma_f32 v60, v78, v60, v61
	global_store_dword v[74:75], v60, off
	v_or_b32_e32 v60, 0x200, v76
	v_mov_b32_e32 v61, v77
	v_lshl_add_u64 v[60:61], v[60:61], 0, v[70:71]
	v_lshlrev_b64 v[60:61], 2, v[60:61]
	v_lshl_add_u64 v[84:85], s[2:3], 0, v[60:61]
	global_load_dword v79, v[84:85], off
	v_lshl_add_u64 v[86:87], s[0:1], 0, v[60:61]
	v_or_b32_e32 v60, 0x300, v76
	v_mov_b32_e32 v61, v77
	v_lshl_add_u64 v[60:61], v[60:61], 0, v[70:71]
	v_lshlrev_b64 v[60:61], 2, v[60:61]
	v_lshl_add_u64 v[88:89], s[2:3], 0, v[60:61]
	v_lshl_add_u64 v[90:91], s[0:1], 0, v[60:61]
	v_lshl_add_u64 v[60:61], v[92:93], 1, v[64:65]
	s_waitcnt vmcnt(0)
	v_fma_f32 v62, v79, v80, v62
	global_store_dword v[86:87], v62, off
	global_load_dword v80, v[88:89], off
	v_mul_f32_e32 v62, 0x3fb8aa3b, v81
	v_exp_f32_e32 v62, v62
	s_waitcnt vmcnt(0)
	v_fmac_f32_e32 v63, v80, v62
	global_store_dword v[90:91], v63, off
	v_cvt_pk_bf16_f32 v62, v69, v78
	v_cvt_pk_bf16_f32 v63, v79, v80
	global_store_dwordx2 v[60:61], v[62:63], off
	global_load_dword v62, v[66:67], off offset:64
	ds_read_b128 v[78:81], v68 offset:6144
	s_waitcnt lgkmcnt(0)
	v_mul_f32_e32 v63, 0x3fb8aa3b, v78
	v_exp_f32_e32 v63, v63
	s_waitcnt vmcnt(0)
	v_fma_f32 v56, v62, v63, v56
	global_store_dword v[72:73], v56, off offset:64
	global_load_dword v56, v[82:83], off offset:64
	v_mul_f32_e32 v63, 0x3fb8aa3b, v79
	v_exp_f32_e32 v63, v63
	v_or_b32_e32 v72, 0x1100, v76
	v_mov_b32_e32 v73, v77
	v_lshl_add_u64 v[72:73], v[72:73], 0, v[70:71]
	v_lshlrev_b64 v[72:73], 2, v[72:73]
	s_waitcnt vmcnt(0)
	v_fma_f32 v57, v56, v63, v57
	global_store_dword v[74:75], v57, off offset:64
	global_load_dword v57, v[84:85], off offset:64
	v_mul_f32_e32 v63, 0x3fb8aa3b, v80
	v_exp_f32_e32 v63, v63
	v_lshl_add_u64 v[74:75], s[2:3], 0, v[72:73]
	s_waitcnt vmcnt(0)
	v_fma_f32 v58, v57, v63, v58
	global_store_dword v[86:87], v58, off offset:64
	global_load_dword v63, v[88:89], off offset:64
	v_mul_f32_e32 v58, 0x3fb8aa3b, v81
	v_exp_f32_e32 v58, v58
	s_waitcnt vmcnt(0)
	v_fmac_f32_e32 v59, v63, v58
	v_cvt_pk_bf16_f32 v58, v62, v56
	v_or_b32_e32 v56, 0x800, v92
	global_store_dword v[90:91], v59, off offset:64
	v_cvt_pk_bf16_f32 v59, v57, v63
	v_ashrrev_i32_e32 v57, 31, v56
	v_lshl_add_u64 v[56:57], v[56:57], 1, v[64:65]
	global_store_dwordx2 v[56:57], v[58:59], off
	v_or_b32_e32 v58, 0x1000, v76
	v_mov_b32_e32 v59, v77
	v_lshl_add_u64 v[58:59], v[58:59], 0, v[70:71]
	v_lshlrev_b64 v[58:59], 2, v[58:59]
	v_lshl_add_u64 v[66:67], s[2:3], 0, v[58:59]
	global_load_dword v69, v[66:67], off
	ds_read_b128 v[62:65], v68 offset:6208
	v_lshl_add_u64 v[58:59], s[0:1], 0, v[58:59]
	s_waitcnt lgkmcnt(0)
	v_mul_f32_e32 v62, 0x3fb8aa3b, v62
	v_exp_f32_e32 v62, v62
	v_mul_f32_e32 v64, 0x3fb8aa3b, v64
	v_exp_f32_e32 v64, v64
	s_waitcnt vmcnt(0)
	v_fma_f32 v52, v69, v62, v52
	global_store_dword v[58:59], v52, off
	global_load_dword v82, v[74:75], off
	v_mul_f32_e32 v52, 0x3fb8aa3b, v63
	v_exp_f32_e32 v52, v52
	v_lshl_add_u64 v[62:63], s[0:1], 0, v[72:73]
	s_waitcnt vmcnt(0)
	v_fma_f32 v52, v82, v52, v53
	global_store_dword v[62:63], v52, off
	v_or_b32_e32 v52, 0x1200, v76
	v_mov_b32_e32 v53, v77
	v_lshl_add_u64 v[52:53], v[52:53], 0, v[70:71]
	v_lshlrev_b64 v[52:53], 2, v[52:53]
	v_lshl_add_u64 v[72:73], s[2:3], 0, v[52:53]
	global_load_dword v83, v[72:73], off
	v_lshl_add_u64 v[78:79], s[0:1], 0, v[52:53]
	v_or_b32_e32 v52, 0x1300, v76
	v_mov_b32_e32 v53, v77
	v_lshl_add_u64 v[52:53], v[52:53], 0, v[70:71]
	v_lshlrev_b64 v[52:53], 2, v[52:53]
	v_lshl_add_u64 v[80:81], s[2:3], 0, v[52:53]
	s_waitcnt vmcnt(0)
	v_fma_f32 v54, v83, v64, v54
	global_store_dword v[78:79], v54, off
	global_load_dword v54, v[80:81], off
	v_mul_f32_e32 v64, 0x3fb8aa3b, v65
	v_exp_f32_e32 v64, v64
	s_waitcnt vmcnt(0)
	v_fmac_f32_e32 v55, v54, v64
	v_lshl_add_u64 v[64:65], s[0:1], 0, v[52:53]
	global_store_dword v[64:65], v55, off
	v_cvt_pk_bf16_f32 v52, v69, v82
	v_cvt_pk_bf16_f32 v53, v83, v54
	global_store_dwordx2 v[60:61], v[52:53], off offset:32
	global_load_dword v66, v[66:67], off offset:64
	ds_read_b128 v[52:55], v68 offset:6208
	s_waitcnt lgkmcnt(0)
	v_mul_f32_e32 v52, 0x3fb8aa3b, v52
	v_exp_f32_e32 v52, v52
	s_waitcnt vmcnt(0)
	v_fma_f32 v48, v66, v52, v48
	global_store_dword v[58:59], v48, off offset:64
	global_load_dword v48, v[74:75], off offset:64
	v_mul_f32_e32 v52, 0x3fb8aa3b, v53
	v_exp_f32_e32 v52, v52
	v_or_b32_e32 v58, 0x2100, v76
	v_mov_b32_e32 v59, v77
	v_lshl_add_u64 v[58:59], v[58:59], 0, v[70:71]
	v_lshlrev_b64 v[58:59], 2, v[58:59]
	s_waitcnt vmcnt(0)
	v_fma_f32 v49, v48, v52, v49
	global_store_dword v[62:63], v49, off offset:64
	global_load_dword v49, v[72:73], off offset:64
	v_mul_f32_e32 v52, 0x3fb8aa3b, v54
	v_exp_f32_e32 v52, v52
	v_cvt_pk_bf16_f32 v48, v66, v48
	v_lshl_add_u64 v[62:63], s[2:3], 0, v[58:59]
	s_waitcnt vmcnt(0)
	v_fma_f32 v50, v49, v52, v50
	global_store_dword v[78:79], v50, off offset:64
	global_load_dword v50, v[80:81], off offset:64
	v_mul_f32_e32 v52, 0x3fb8aa3b, v55
	v_exp_f32_e32 v52, v52
	s_waitcnt vmcnt(0)
; __device__ __forceinline__ unsigned cvt_pk(float lo, float hi) { unsigned r; asm("v_cvt_pk_bf16_f32 %0, %1, %2" : "=v"(r) : "v"(lo), "v"(hi)); return r; }
; __device__ __forceinline__ void gla_a_item(unsigned char* lds, const Params& p, int item) {
;     ...
;         for (int kb = 0; kb < 8; ++kb)
; #pragma unroll
;             for (int v = 0; v < 2; ++v) { const int vdim = 16 * (2 * wave + v) + li, kdim = 16 * kb + 4 * fq; float s0[4];
; #pragma unroll
;                 for (int r = 0; r < 4; ++r) { s0[r] = s0p[(size_t)(kdim + r) * 256 + vdim]; so[(size_t)(kdim + r) * 256 + vdim] = s0[r] * __expf(bl[kdim + r]) + acc[kb][v][r]; }
;                 u32x2 w; w.x = cvt_pk(s0[0], s0[1]); w.y = cvt_pk(s0[2], s0[3]); *(u32x2*)(STS + vdim * 128 + kdim) = w; asm volatile("" ::: "memory"); }
	v_cvt_pk_bf16_f32 v49, v49, v50
	v_fmac_f32_e32 v51, v50, v52
	global_store_dword v[64:65], v51, off offset:64
	global_store_dwordx2 v[56:57], v[48:49], off offset:32
	v_or_b32_e32 v48, 0x2000, v76
	v_mov_b32_e32 v49, v77
	v_lshl_add_u64 v[48:49], v[48:49], 0, v[70:71]
	v_lshlrev_b64 v[52:53], 2, v[48:49]
	v_lshl_add_u64 v[54:55], s[2:3], 0, v[52:53]
	global_load_dword v69, v[54:55], off
	ds_read_b128 v[48:51], v68 offset:6272
	v_lshl_add_u64 v[52:53], s[0:1], 0, v[52:53]
	s_waitcnt lgkmcnt(0)
	v_mul_f32_e32 v48, 0x3fb8aa3b, v48
	v_exp_f32_e32 v48, v48
	v_mul_f32_e32 v50, 0x3fb8aa3b, v50
	v_exp_f32_e32 v50, v50
	s_waitcnt vmcnt(0)
	v_fma_f32 v44, v69, v48, v44
	global_store_dword v[52:53], v44, off
	global_load_dword v72, v[62:63], off
	v_mul_f32_e32 v44, 0x3fb8aa3b, v49
	v_exp_f32_e32 v44, v44
	v_lshl_add_u64 v[48:49], s[0:1], 0, v[58:59]
	s_waitcnt vmcnt(0)
	v_fma_f32 v44, v72, v44, v45
	global_store_dword v[48:49], v44, off
	v_or_b32_e32 v44, 0x2200, v76
	v_mov_b32_e32 v45, v77
	v_lshl_add_u64 v[44:45], v[44:45], 0, v[70:71]
	v_lshlrev_b64 v[44:45], 2, v[44:45]
	v_lshl_add_u64 v[58:59], s[2:3], 0, v[44:45]
	global_load_dword v73, v[58:59], off
	v_lshl_add_u64 v[64:65], s[0:1], 0, v[44:45]
	v_or_b32_e32 v44, 0x2300, v76
	v_mov_b32_e32 v45, v77
	v_lshl_add_u64 v[44:45], v[44:45], 0, v[70:71]
	v_lshlrev_b64 v[44:45], 2, v[44:45]
	v_lshl_add_u64 v[66:67], s[2:3], 0, v[44:45]
	s_waitcnt vmcnt(0)
	v_fma_f32 v46, v73, v50, v46
	global_store_dword v[64:65], v46, off
	global_load_dword v46, v[66:67], off
	v_mul_f32_e32 v50, 0x3fb8aa3b, v51
	v_exp_f32_e32 v50, v50
	s_waitcnt vmcnt(0)
	v_fmac_f32_e32 v47, v46, v50
	v_lshl_add_u64 v[50:51], s[0:1], 0, v[44:45]
	global_store_dword v[50:51], v47, off
	v_cvt_pk_bf16_f32 v44, v69, v72
	v_cvt_pk_bf16_f32 v45, v73, v46
	global_store_dwordx2 v[60:61], v[44:45], off offset:64
	global_load_dword v54, v[54:55], off offset:64
	ds_read_b128 v[44:47], v68 offset:6272
	s_waitcnt lgkmcnt(0)
	v_mul_f32_e32 v44, 0x3fb8aa3b, v44
	v_exp_f32_e32 v44, v44
	s_waitcnt vmcnt(0)
	v_fma_f32 v40, v54, v44, v40
	global_store_dword v[52:53], v40, off offset:64
	global_load_dword v40, v[62:63], off offset:64
	v_mul_f32_e32 v44, 0x3fb8aa3b, v45
	v_exp_f32_e32 v44, v44
	s_waitcnt vmcnt(0)
	v_fma_f32 v41, v40, v44, v41
	global_store_dword v[48:49], v41, off offset:64
	global_load_dword v41, v[58:59], off offset:64
	v_mul_f32_e32 v44, 0x3fb8aa3b, v46
	v_exp_f32_e32 v44, v44
	v_cvt_pk_bf16_f32 v40, v54, v40
	v_or_b32_e32 v48, 0x3100, v76
	v_mov_b32_e32 v49, v77
	v_lshl_add_u64 v[48:49], v[48:49], 0, v[70:71]
	v_lshlrev_b64 v[48:49], 2, v[48:49]
	s_waitcnt vmcnt(0)
	v_fma_f32 v42, v41, v44, v42
	global_store_dword v[64:65], v42, off offset:64
	global_load_dword v42, v[66:67], off offset:64
	v_mul_f32_e32 v44, 0x3fb8aa3b, v47
	v_exp_f32_e32 v44, v44
	s_waitcnt vmcnt(0)
	v_cvt_pk_bf16_f32 v41, v41, v42
	v_fmac_f32_e32 v43, v42, v44
	global_store_dword v[50:51], v43, off offset:64
	global_store_dwordx2 v[56:57], v[40:41], off offset:64
	v_or_b32_e32 v40, 0x3000, v76
	v_mov_b32_e32 v41, v77
	v_lshl_add_u64 v[40:41], v[40:41], 0, v[70:71]
	v_lshlrev_b64 v[44:45], 2, v[40:41]
	v_lshl_add_u64 v[46:47], s[2:3], 0, v[44:45]
	global_load_dword v58, v[46:47], off
	ds_read_b128 v[40:43], v68 offset:6336
	v_lshl_add_u64 v[44:45], s[0:1], 0, v[44:45]
	v_lshl_add_u64 v[50:51], s[2:3], 0, v[48:49]
	s_waitcnt lgkmcnt(0)
	v_mul_f32_e32 v40, 0x3fb8aa3b, v40
	v_exp_f32_e32 v40, v40
	v_mul_f32_e32 v42, 0x3fb8aa3b, v42
	v_exp_f32_e32 v42, v42
	s_waitcnt vmcnt(0)
	v_fma_f32 v36, v58, v40, v36
	global_store_dword v[44:45], v36, off
	global_load_dword v59, v[50:51], off
	v_mul_f32_e32 v36, 0x3fb8aa3b, v41
	v_exp_f32_e32 v36, v36
	v_lshl_add_u64 v[40:41], s[0:1], 0, v[48:49]
	s_waitcnt vmcnt(0)
	v_fma_f32 v36, v59, v36, v37
	global_store_dword v[40:41], v36, off
	v_or_b32_e32 v36, 0x3200, v76
	v_mov_b32_e32 v37, v77
	v_lshl_add_u64 v[36:37], v[36:37], 0, v[70:71]
	v_lshlrev_b64 v[36:37], 2, v[36:37]
	v_lshl_add_u64 v[48:49], s[2:3], 0, v[36:37]
	global_load_dword v62, v[48:49], off
	v_lshl_add_u64 v[52:53], s[0:1], 0, v[36:37]
	v_or_b32_e32 v36, 0x3300, v76
	v_mov_b32_e32 v37, v77
	v_lshl_add_u64 v[36:37], v[36:37], 0, v[70:71]
	v_lshlrev_b64 v[36:37], 2, v[36:37]
	v_lshl_add_u64 v[54:55], s[2:3], 0, v[36:37]
	s_waitcnt vmcnt(0)
	v_fma_f32 v38, v62, v42, v38
	global_store_dword v[52:53], v38, off
	global_load_dword v38, v[54:55], off
	v_mul_f32_e32 v42, 0x3fb8aa3b, v43
	v_exp_f32_e32 v42, v42
	s_waitcnt vmcnt(0)
	v_fmac_f32_e32 v39, v38, v42
	v_lshl_add_u64 v[42:43], s[0:1], 0, v[36:37]
	global_store_dword v[42:43], v39, off
	v_cvt_pk_bf16_f32 v36, v58, v59
	v_cvt_pk_bf16_f32 v37, v62, v38
	global_store_dwordx2 v[60:61], v[36:37], off offset:96
	global_load_dword v46, v[46:47], off offset:64
	ds_read_b128 v[36:39], v68 offset:6336
	s_waitcnt lgkmcnt(0)
	v_mul_f32_e32 v36, 0x3fb8aa3b, v36
	v_exp_f32_e32 v36, v36
	s_waitcnt vmcnt(0)
	v_fma_f32 v32, v46, v36, v32
	global_store_dword v[44:45], v32, off offset:64
	global_load_dword v32, v[50:51], off offset:64
	v_mul_f32_e32 v36, 0x3fb8aa3b, v37
	v_exp_f32_e32 v36, v36
	s_waitcnt vmcnt(0)
	v_fma_f32 v33, v32, v36, v33
	global_store_dword v[40:41], v33, off offset:64
	global_load_dword v33, v[48:49], off offset:64
	v_mul_f32_e32 v36, 0x3fb8aa3b, v38
	v_exp_f32_e32 v36, v36
	v_cvt_pk_bf16_f32 v32, v46, v32
	v_or_b32_e32 v40, 0x4100, v76
	v_mov_b32_e32 v41, v77
	v_lshl_add_u64 v[40:41], v[40:41], 0, v[70:71]
	v_lshlrev_b64 v[40:41], 2, v[40:41]
	s_waitcnt vmcnt(0)
	v_fma_f32 v34, v33, v36, v34
	global_store_dword v[52:53], v34, off offset:64
	global_load_dword v34, v[54:55], off offset:64
	v_mul_f32_e32 v36, 0x3fb8aa3b, v39
	v_exp_f32_e32 v36, v36
	s_waitcnt vmcnt(0)
; __device__ __forceinline__ unsigned cvt_pk(float lo, float hi) { unsigned r; asm("v_cvt_pk_bf16_f32 %0, %1, %2" : "=v"(r) : "v"(lo), "v"(hi)); return r; }
; __device__ __forceinline__ void gla_a_item(unsigned char* lds, const Params& p, int item) {
;     ...
;         for (int kb = 0; kb < 8; ++kb)
; #pragma unroll
;             for (int v = 0; v < 2; ++v) { const int vdim = 16 * (2 * wave + v) + li, kdim = 16 * kb + 4 * fq; float s0[4];
; #pragma unroll
;                 for (int r = 0; r < 4; ++r) { s0[r] = s0p[(size_t)(kdim + r) * 256 + vdim]; so[(size_t)(kdim + r) * 256 + vdim] = s0[r] * __expf(bl[kdim + r]) + acc[kb][v][r]; }
;                 u32x2 w; w.x = cvt_pk(s0[0], s0[1]); w.y = cvt_pk(s0[2], s0[3]); *(u32x2*)(STS + vdim * 128 + kdim) = w; asm volatile("" ::: "memory"); }
	v_cvt_pk_bf16_f32 v33, v33, v34
	v_fmac_f32_e32 v35, v34, v36
	global_store_dword v[42:43], v35, off offset:64
	global_store_dwordx2 v[56:57], v[32:33], off offset:96
	v_or_b32_e32 v32, 0x4000, v76
	v_mov_b32_e32 v33, v77
	v_lshl_add_u64 v[32:33], v[32:33], 0, v[70:71]
	v_lshlrev_b64 v[36:37], 2, v[32:33]
	v_lshl_add_u64 v[38:39], s[2:3], 0, v[36:37]
	global_load_dword v48, v[38:39], off
	ds_read_b128 v[32:35], v68 offset:6400
	v_lshl_add_u64 v[36:37], s[0:1], 0, v[36:37]
	v_lshl_add_u64 v[42:43], s[2:3], 0, v[40:41]
	s_waitcnt lgkmcnt(0)
	v_mul_f32_e32 v32, 0x3fb8aa3b, v32
	v_exp_f32_e32 v32, v32
	v_mul_f32_e32 v34, 0x3fb8aa3b, v34
	v_exp_f32_e32 v34, v34
	s_waitcnt vmcnt(0)
	v_fma_f32 v28, v48, v32, v28
	global_store_dword v[36:37], v28, off
	global_load_dword v49, v[42:43], off
	v_mul_f32_e32 v28, 0x3fb8aa3b, v33
	v_exp_f32_e32 v28, v28
	v_lshl_add_u64 v[32:33], s[0:1], 0, v[40:41]
	s_waitcnt vmcnt(0)
	v_fma_f32 v28, v49, v28, v29
	global_store_dword v[32:33], v28, off
	v_or_b32_e32 v28, 0x4200, v76
	v_mov_b32_e32 v29, v77
	v_lshl_add_u64 v[28:29], v[28:29], 0, v[70:71]
	v_lshlrev_b64 v[28:29], 2, v[28:29]
	v_lshl_add_u64 v[40:41], s[2:3], 0, v[28:29]
	global_load_dword v50, v[40:41], off
	v_lshl_add_u64 v[44:45], s[0:1], 0, v[28:29]
	v_or_b32_e32 v28, 0x4300, v76
	v_mov_b32_e32 v29, v77
	v_lshl_add_u64 v[28:29], v[28:29], 0, v[70:71]
	v_lshlrev_b64 v[28:29], 2, v[28:29]
	v_lshl_add_u64 v[46:47], s[2:3], 0, v[28:29]
	s_waitcnt vmcnt(0)
	v_fma_f32 v30, v50, v34, v30
	global_store_dword v[44:45], v30, off
	global_load_dword v30, v[46:47], off
	v_mul_f32_e32 v34, 0x3fb8aa3b, v35
	v_exp_f32_e32 v34, v34
	s_waitcnt vmcnt(0)
	v_fmac_f32_e32 v31, v30, v34
	v_lshl_add_u64 v[34:35], s[0:1], 0, v[28:29]
	global_store_dword v[34:35], v31, off
	v_cvt_pk_bf16_f32 v28, v48, v49
	v_cvt_pk_bf16_f32 v29, v50, v30
	global_store_dwordx2 v[60:61], v[28:29], off offset:128
	global_load_dword v38, v[38:39], off offset:64
	ds_read_b128 v[28:31], v68 offset:6400
	s_waitcnt lgkmcnt(0)
	v_mul_f32_e32 v28, 0x3fb8aa3b, v28
	v_exp_f32_e32 v28, v28
	s_waitcnt vmcnt(0)
	v_fma_f32 v24, v38, v28, v24
	global_store_dword v[36:37], v24, off offset:64
	global_load_dword v24, v[42:43], off offset:64
	v_mul_f32_e32 v28, 0x3fb8aa3b, v29
	v_exp_f32_e32 v28, v28
	s_waitcnt vmcnt(0)
	v_fma_f32 v25, v24, v28, v25
	global_store_dword v[32:33], v25, off offset:64
	global_load_dword v25, v[40:41], off offset:64
	v_mul_f32_e32 v28, 0x3fb8aa3b, v30
	v_exp_f32_e32 v28, v28
	v_cvt_pk_bf16_f32 v24, v38, v24
	v_or_b32_e32 v32, 0x5100, v76
	v_mov_b32_e32 v33, v77
	v_lshl_add_u64 v[32:33], v[32:33], 0, v[70:71]
	v_lshlrev_b64 v[32:33], 2, v[32:33]
	s_waitcnt vmcnt(0)
	v_fma_f32 v26, v25, v28, v26
	global_store_dword v[44:45], v26, off offset:64
	global_load_dword v26, v[46:47], off offset:64
	v_mul_f32_e32 v28, 0x3fb8aa3b, v31
	v_exp_f32_e32 v28, v28
	s_waitcnt vmcnt(0)
	v_cvt_pk_bf16_f32 v25, v25, v26
	v_fmac_f32_e32 v27, v26, v28
	global_store_dword v[34:35], v27, off offset:64
	global_store_dwordx2 v[56:57], v[24:25], off offset:128
	v_or_b32_e32 v24, 0x5000, v76
	v_mov_b32_e32 v25, v77
	v_lshl_add_u64 v[24:25], v[24:25], 0, v[70:71]
	v_lshlrev_b64 v[28:29], 2, v[24:25]
	v_lshl_add_u64 v[30:31], s[2:3], 0, v[28:29]
	global_load_dword v40, v[30:31], off
	ds_read_b128 v[24:27], v68 offset:6464
	v_lshl_add_u64 v[28:29], s[0:1], 0, v[28:29]
	v_lshl_add_u64 v[34:35], s[2:3], 0, v[32:33]
	s_waitcnt lgkmcnt(0)
	v_mul_f32_e32 v24, 0x3fb8aa3b, v24
	v_exp_f32_e32 v24, v24
	v_mul_f32_e32 v26, 0x3fb8aa3b, v26
	v_exp_f32_e32 v26, v26
	s_waitcnt vmcnt(0)
	v_fma_f32 v20, v40, v24, v20
	global_store_dword v[28:29], v20, off
	global_load_dword v41, v[34:35], off
	v_mul_f32_e32 v20, 0x3fb8aa3b, v25
	v_exp_f32_e32 v20, v20
	v_lshl_add_u64 v[24:25], s[0:1], 0, v[32:33]
	s_waitcnt vmcnt(0)
	v_fma_f32 v20, v41, v20, v21
	global_store_dword v[24:25], v20, off
	v_or_b32_e32 v20, 0x5200, v76
	v_mov_b32_e32 v21, v77
	v_lshl_add_u64 v[20:21], v[20:21], 0, v[70:71]
	v_lshlrev_b64 v[20:21], 2, v[20:21]
	v_lshl_add_u64 v[32:33], s[2:3], 0, v[20:21]
	global_load_dword v42, v[32:33], off
	v_lshl_add_u64 v[36:37], s[0:1], 0, v[20:21]
	v_or_b32_e32 v20, 0x5300, v76
	v_mov_b32_e32 v21, v77
	v_lshl_add_u64 v[20:21], v[20:21], 0, v[70:71]
	v_lshlrev_b64 v[20:21], 2, v[20:21]
	v_lshl_add_u64 v[38:39], s[2:3], 0, v[20:21]
	s_waitcnt vmcnt(0)
	v_fma_f32 v22, v42, v26, v22
	global_store_dword v[36:37], v22, off
	global_load_dword v22, v[38:39], off
	v_mul_f32_e32 v26, 0x3fb8aa3b, v27
	v_exp_f32_e32 v26, v26
	s_waitcnt vmcnt(0)
	v_fmac_f32_e32 v23, v22, v26
	v_lshl_add_u64 v[26:27], s[0:1], 0, v[20:21]
	global_store_dword v[26:27], v23, off
	v_cvt_pk_bf16_f32 v20, v40, v41
	v_cvt_pk_bf16_f32 v21, v42, v22
	global_store_dwordx2 v[60:61], v[20:21], off offset:160
	global_load_dword v30, v[30:31], off offset:64
	ds_read_b128 v[20:23], v68 offset:6464
	s_waitcnt lgkmcnt(0)
	v_mul_f32_e32 v20, 0x3fb8aa3b, v20
	v_exp_f32_e32 v20, v20
	s_waitcnt vmcnt(0)
	v_fma_f32 v16, v30, v20, v16
	global_store_dword v[28:29], v16, off offset:64
	global_load_dword v16, v[34:35], off offset:64
	v_mul_f32_e32 v20, 0x3fb8aa3b, v21
	v_exp_f32_e32 v20, v20
	s_waitcnt vmcnt(0)
	v_fma_f32 v17, v16, v20, v17
	global_store_dword v[24:25], v17, off offset:64
	global_load_dword v17, v[32:33], off offset:64
	v_mul_f32_e32 v20, 0x3fb8aa3b, v22
	v_exp_f32_e32 v20, v20
	v_cvt_pk_bf16_f32 v16, v30, v16
	v_or_b32_e32 v24, 0x6100, v76
	v_mov_b32_e32 v25, v77
	v_lshl_add_u64 v[24:25], v[24:25], 0, v[70:71]
	v_lshlrev_b64 v[24:25], 2, v[24:25]
	s_waitcnt vmcnt(0)
; __device__ __forceinline__ unsigned cvt_pk(float lo, float hi) { unsigned r; asm("v_cvt_pk_bf16_f32 %0, %1, %2" : "=v"(r) : "v"(lo), "v"(hi)); return r; }
; __device__ __forceinline__ void gla_a_item(unsigned char* lds, const Params& p, int item) {
;     ...
;         for (int kb = 0; kb < 8; ++kb)
; #pragma unroll
;             for (int v = 0; v < 2; ++v) { const int vdim = 16 * (2 * wave + v) + li, kdim = 16 * kb + 4 * fq; float s0[4];
; #pragma unroll
;                 for (int r = 0; r < 4; ++r) { s0[r] = s0p[(size_t)(kdim + r) * 256 + vdim]; so[(size_t)(kdim + r) * 256 + vdim] = s0[r] * __expf(bl[kdim + r]) + acc[kb][v][r]; }
;                 u32x2 w; w.x = cvt_pk(s0[0], s0[1]); w.y = cvt_pk(s0[2], s0[3]); *(u32x2*)(STS + vdim * 128 + kdim) = w; asm volatile("" ::: "memory"); }
	v_fma_f32 v18, v17, v20, v18
	global_store_dword v[36:37], v18, off offset:64
	global_load_dword v18, v[38:39], off offset:64
	v_mul_f32_e32 v20, 0x3fb8aa3b, v23
	v_exp_f32_e32 v20, v20
	s_waitcnt vmcnt(0)
	v_cvt_pk_bf16_f32 v17, v17, v18
	v_fmac_f32_e32 v19, v18, v20
	global_store_dword v[26:27], v19, off offset:64
	global_store_dwordx2 v[56:57], v[16:17], off offset:160
	v_or_b32_e32 v16, 0x6000, v76
	v_mov_b32_e32 v17, v77
	v_lshl_add_u64 v[16:17], v[16:17], 0, v[70:71]
	v_lshlrev_b64 v[20:21], 2, v[16:17]
	v_lshl_add_u64 v[22:23], s[2:3], 0, v[20:21]
	global_load_dword v32, v[22:23], off
	ds_read_b128 v[16:19], v68 offset:6528
	v_lshl_add_u64 v[20:21], s[0:1], 0, v[20:21]
	v_lshl_add_u64 v[26:27], s[2:3], 0, v[24:25]
	s_waitcnt lgkmcnt(0)
	v_mul_f32_e32 v16, 0x3fb8aa3b, v16
	v_exp_f32_e32 v16, v16
	v_mul_f32_e32 v18, 0x3fb8aa3b, v18
	v_exp_f32_e32 v18, v18
	s_waitcnt vmcnt(0)
	v_fma_f32 v12, v32, v16, v12
	global_store_dword v[20:21], v12, off
	global_load_dword v33, v[26:27], off
	v_mul_f32_e32 v12, 0x3fb8aa3b, v17
	v_exp_f32_e32 v12, v12
	v_lshl_add_u64 v[16:17], s[0:1], 0, v[24:25]
	s_waitcnt vmcnt(0)
	v_fma_f32 v12, v33, v12, v13
	global_store_dword v[16:17], v12, off
	v_or_b32_e32 v12, 0x6200, v76
	v_mov_b32_e32 v13, v77
	v_lshl_add_u64 v[12:13], v[12:13], 0, v[70:71]
	v_lshlrev_b64 v[12:13], 2, v[12:13]
	v_lshl_add_u64 v[24:25], s[2:3], 0, v[12:13]
	global_load_dword v34, v[24:25], off
	v_lshl_add_u64 v[28:29], s[0:1], 0, v[12:13]
	v_or_b32_e32 v12, 0x6300, v76
	v_mov_b32_e32 v13, v77
	v_lshl_add_u64 v[12:13], v[12:13], 0, v[70:71]
	v_lshlrev_b64 v[12:13], 2, v[12:13]
	v_lshl_add_u64 v[30:31], s[2:3], 0, v[12:13]
	s_waitcnt vmcnt(0)
	v_fma_f32 v14, v34, v18, v14
	global_store_dword v[28:29], v14, off
	global_load_dword v14, v[30:31], off
	v_mul_f32_e32 v18, 0x3fb8aa3b, v19
	v_exp_f32_e32 v18, v18
	s_waitcnt vmcnt(0)
	v_fmac_f32_e32 v15, v14, v18
	v_lshl_add_u64 v[18:19], s[0:1], 0, v[12:13]
	global_store_dword v[18:19], v15, off
	v_cvt_pk_bf16_f32 v12, v32, v33
	v_cvt_pk_bf16_f32 v13, v34, v14
	global_store_dwordx2 v[60:61], v[12:13], off offset:192
	global_load_dword v22, v[22:23], off offset:64
	ds_read_b128 v[12:15], v68 offset:6528
	s_waitcnt lgkmcnt(0)
	v_mul_f32_e32 v12, 0x3fb8aa3b, v12
	v_exp_f32_e32 v12, v12
	s_waitcnt vmcnt(0)
	v_fma_f32 v8, v22, v12, v8
	global_store_dword v[20:21], v8, off offset:64
	global_load_dword v8, v[26:27], off offset:64
	v_mul_f32_e32 v12, 0x3fb8aa3b, v13
	v_exp_f32_e32 v12, v12
	s_waitcnt vmcnt(0)
	v_fma_f32 v9, v8, v12, v9
	global_store_dword v[16:17], v9, off offset:64
	global_load_dword v9, v[24:25], off offset:64
	v_mul_f32_e32 v12, 0x3fb8aa3b, v14
	v_exp_f32_e32 v12, v12
	v_cvt_pk_bf16_f32 v8, v22, v8
	v_or_b32_e32 v16, 0x7100, v76
	v_mov_b32_e32 v17, v77
	v_lshl_add_u64 v[16:17], v[16:17], 0, v[70:71]
	v_lshlrev_b64 v[16:17], 2, v[16:17]
	s_waitcnt vmcnt(0)
	v_fma_f32 v10, v9, v12, v10
	global_store_dword v[28:29], v10, off offset:64
	global_load_dword v10, v[30:31], off offset:64
	v_mul_f32_e32 v12, 0x3fb8aa3b, v15
	v_exp_f32_e32 v12, v12
	s_waitcnt vmcnt(0)
	v_cvt_pk_bf16_f32 v9, v9, v10
	v_fmac_f32_e32 v11, v10, v12
	global_store_dword v[18:19], v11, off offset:64
	global_store_dwordx2 v[56:57], v[8:9], off offset:192
	v_or_b32_e32 v8, 0x7000, v76
	v_mov_b32_e32 v9, v77
	v_lshl_add_u64 v[8:9], v[8:9], 0, v[70:71]
	v_lshlrev_b64 v[12:13], 2, v[8:9]
	v_lshl_add_u64 v[14:15], s[2:3], 0, v[12:13]
	global_load_dword v24, v[14:15], off
	ds_read_b128 v[8:11], v68 offset:6592
	v_lshl_add_u64 v[12:13], s[0:1], 0, v[12:13]
	v_lshl_add_u64 v[18:19], s[2:3], 0, v[16:17]
	s_waitcnt lgkmcnt(0)
	v_mul_f32_e32 v8, 0x3fb8aa3b, v8
	v_exp_f32_e32 v8, v8
	v_mul_f32_e32 v10, 0x3fb8aa3b, v10
	v_exp_f32_e32 v10, v10
	s_waitcnt vmcnt(0)
	v_fma_f32 v4, v24, v8, v4
	global_store_dword v[12:13], v4, off
	global_load_dword v25, v[18:19], off
	v_mul_f32_e32 v4, 0x3fb8aa3b, v9
	v_exp_f32_e32 v4, v4
	v_lshl_add_u64 v[8:9], s[0:1], 0, v[16:17]
	s_waitcnt vmcnt(0)
	v_fma_f32 v4, v25, v4, v5
	global_store_dword v[8:9], v4, off
	v_or_b32_e32 v4, 0x7200, v76
	v_mov_b32_e32 v5, v77
	v_lshl_add_u64 v[4:5], v[4:5], 0, v[70:71]
	v_lshlrev_b64 v[4:5], 2, v[4:5]
	v_lshl_add_u64 v[16:17], s[2:3], 0, v[4:5]
	global_load_dword v26, v[16:17], off
	v_or_b32_e32 v76, 0x7300, v76
	v_lshl_add_u64 v[20:21], s[0:1], 0, v[4:5]
	v_lshl_add_u64 v[4:5], v[76:77], 0, v[70:71]
	v_lshlrev_b64 v[4:5], 2, v[4:5]
	v_lshl_add_u64 v[22:23], s[2:3], 0, v[4:5]
	s_waitcnt vmcnt(0)
	v_fma_f32 v6, v26, v10, v6
	global_store_dword v[20:21], v6, off
	global_load_dword v6, v[22:23], off
	v_mul_f32_e32 v10, 0x3fb8aa3b, v11
	v_exp_f32_e32 v10, v10
	s_waitcnt vmcnt(0)
	v_fmac_f32_e32 v7, v6, v10
	v_lshl_add_u64 v[10:11], s[0:1], 0, v[4:5]
	global_store_dword v[10:11], v7, off
	v_cvt_pk_bf16_f32 v4, v24, v25
	v_cvt_pk_bf16_f32 v5, v26, v6
	global_store_dwordx2 v[60:61], v[4:5], off offset:224
	global_load_dword v14, v[14:15], off offset:64
	ds_read_b128 v[4:7], v68 offset:6592
	s_waitcnt lgkmcnt(0)
	v_mul_f32_e32 v4, 0x3fb8aa3b, v4
	v_exp_f32_e32 v4, v4
	s_waitcnt vmcnt(0)
	v_fma_f32 v0, v14, v4, v0
	global_store_dword v[12:13], v0, off offset:64
	global_load_dword v0, v[18:19], off offset:64
	v_mul_f32_e32 v4, 0x3fb8aa3b, v5
	v_exp_f32_e32 v4, v4
	s_waitcnt vmcnt(0)
	v_fma_f32 v1, v0, v4, v1
	global_store_dword v[8:9], v1, off offset:64
	global_load_dword v1, v[16:17], off offset:64
	v_mul_f32_e32 v4, 0x3fb8aa3b, v6
	v_exp_f32_e32 v4, v4
	v_cvt_pk_bf16_f32 v0, v14, v0
	s_waitcnt vmcnt(0)
	v_fma_f32 v2, v1, v4, v2
	global_store_dword v[20:21], v2, off offset:64
	global_load_dword v2, v[22:23], off offset:64
	v_mul_f32_e32 v4, 0x3fb8aa3b, v7
	v_exp_f32_e32 v4, v4
	s_waitcnt vmcnt(0)
	v_cvt_pk_bf16_f32 v1, v1, v2
	v_fmac_f32_e32 v3, v2, v4
	global_store_dword v[10:11], v3, off offset:64
	global_store_dwordx2 v[56:57], v[0:1], off offset:224

; __device__ __forceinline__ unsigned cvt_pk(float lo, float hi) { unsigned r; asm("v_cvt_pk_bf16_f32 %0, %1, %2" : "=v"(r) : "v"(lo), "v"(hi)); return r; }
; __device__ __forceinline__ void attn_sample_item(unsigned char* lds, const Params& p, int item, bool dry) {
;     ...
;         if (kt < 8) {
; #pragma unroll
;             for (int ii = 0; ii < 4; ++ii) { const int pc = tid + 512 * ii, row = pc >> 5, c4 = (pc & 31) * 4; const f32x4 v = __builtin_nontemporal_load((const f32x4*)(ck + (size_t)(kt * 64 + row) * 1024 + c4));
;                 u32x2 w; w.x = cvt_pk(v[0], v[1]); w.y = cvt_pk(v[2], v[3]); *(u32x2*)(Kl + row * 136 + c4) = w; }
;             const int d = tid & 127, tq = tid >> 7; unsigned w[8];
; #pragma unroll
;             for (int i2 = 0; i2 < 8; ++i2) { const int key = kt * 64 + 16 * tq + 2 * i2; w[i2] = cvt_pk(cv[(size_t)key * 1024 + d], cv[(size_t)(key + 1) * 1024 + d]); }
;             u32x4* dd = (u32x4*)(VTl + d * 72 + 16 * tq); { u32x4 x = {w[0], w[1], w[2], w[3]}; dd[0] = x; } { u32x4 x = {w[4], w[5], w[6], w[7]}; dd[1] = x; }
.LBB0_785:
	s_cmp_lg_u32 s0, 0x200000
	s_mov_b64 s[70:71], -1
	s_waitcnt lgkmcnt(0)
	s_barrier
	s_cbranch_scc0 .LBB0_787
	v_lshl_add_u64 v[48:49], v[108:109], 0, s[0:1]
	global_load_dwordx4 v[144:147], v[48:49], off nt
	v_lshl_add_u64 v[48:49], v[106:107], 0, s[0:1]
	global_load_dwordx4 v[148:151], v[48:49], off nt
	v_lshl_add_u64 v[48:49], v[104:105], 0, s[0:1]
	global_load_dwordx4 v[152:155], v[48:49], off nt
	v_lshl_add_u64 v[48:49], v[102:103], 0, s[0:1]
	global_load_dwordx4 v[156:159], v[48:49], off nt
	v_lshl_add_u64 v[56:57], v[100:101], 0, s[0:1]
	v_add_co_u32_e32 v50, vcc, 0x1000, v56
	s_nop 1
	v_addc_co_u32_e32 v51, vcc, 0, v57, vcc
	global_load_dword v160, v[50:51], off offset:-4096
	global_load_dword v161, v[50:51], off
	v_add_co_u32_e32 v50, vcc, 0x3000, v56
	s_nop 1
	v_addc_co_u32_e32 v51, vcc, 0, v57, vcc
	global_load_dword v162, v[50:51], off offset:-4096
	global_load_dword v163, v[50:51], off
	v_add_co_u32_e32 v50, vcc, 0x5000, v56
	s_nop 1
	v_addc_co_u32_e32 v51, vcc, 0, v57, vcc
	global_load_dword v164, v[50:51], off offset:-4096
	global_load_dword v165, v[50:51], off
	v_add_co_u32_e32 v50, vcc, 0x7000, v56
	s_nop 1
	v_addc_co_u32_e32 v51, vcc, 0, v57, vcc
	global_load_dword v166, v[50:51], off offset:-4096
	global_load_dword v167, v[50:51], off
	v_add_co_u32_e32 v50, vcc, 0x9000, v56
	s_nop 1
	v_addc_co_u32_e32 v51, vcc, 0, v57, vcc
	global_load_dword v168, v[50:51], off offset:-4096
	global_load_dword v169, v[50:51], off
	v_add_co_u32_e32 v50, vcc, 0xb000, v56
	s_nop 1
	v_addc_co_u32_e32 v51, vcc, 0, v57, vcc
	global_load_dword v170, v[50:51], off offset:-4096
	global_load_dword v171, v[50:51], off
	v_add_co_u32_e32 v50, vcc, 0xd000, v56
	s_nop 1
	v_addc_co_u32_e32 v51, vcc, 0, v57, vcc
	global_load_dword v172, v[50:51], off offset:-4096
	global_load_dword v173, v[50:51], off
	v_add_co_u32_e32 v50, vcc, 0xf000, v56
	s_nop 1
	v_addc_co_u32_e32 v51, vcc, 0, v57, vcc
	global_load_dword v174, v[50:51], off offset:-4096
	global_load_dword v175, v[50:51], off
	s_mov_b32 s26, 0xc000
	s_mov_b64 s[70:71], 0
	s_waitcnt vmcnt(16)
	v_cvt_pk_bf16_f32 v48, v144, v145
	v_cvt_pk_bf16_f32 v49, v146, v147
	ds_write_b64 v121, v[48:49] offset:1280
	v_cvt_pk_bf16_f32 v48, v148, v149
	v_cvt_pk_bf16_f32 v49, v150, v151
	ds_write_b64 v122, v[48:49] offset:1280
	v_cvt_pk_bf16_f32 v48, v152, v153
	v_cvt_pk_bf16_f32 v49, v154, v155
	ds_write_b64 v123, v[48:49] offset:1280
	v_cvt_pk_bf16_f32 v48, v156, v157
	v_cvt_pk_bf16_f32 v49, v158, v159
	ds_write_b64 v124, v[48:49] offset:1280
	s_waitcnt vmcnt(0)
	v_cvt_pk_bf16_f32 v48, v160, v161
	v_cvt_pk_bf16_f32 v49, v162, v163
	v_cvt_pk_bf16_f32 v50, v164, v165
	v_cvt_pk_bf16_f32 v51, v166, v167
	v_cvt_pk_bf16_f32 v52, v168, v169
	v_cvt_pk_bf16_f32 v53, v170, v171
	v_cvt_pk_bf16_f32 v54, v172, v173
	v_cvt_pk_bf16_f32 v55, v174, v175
